# v20 + QKV epilogue: counted waits instead of vmcnt(0) drains between rope batches
# speedup vs baseline: 1.0115x; 1.0067x over previous
; __device__ __forceinline__ u32x4 pack8(f32x4 a, f32x4 b) { u32x4 w; w.x = cvt_pk_bf16(a[0], a[1]); w.y = cvt_pk_bf16(a[2], a[3]); w.z = cvt_pk_bf16(b[0], b[1]); w.w = cvt_pk_bf16(b[2], b[3]); return w; }
; __device__ __forceinline__ bf16x8 pack8(f32x4 a, f32x4 b) { u32x4 w = {cvtpk(a[0], a[1]), cvtpk(a[2], a[3]), cvtpk(b[0], b[1]), cvtpk(b[2], b[3])}; return *reinterpret_cast<bf16x8*>(&w); }
;     PG8_RSTD_HOOKS
;     __device__ __forceinline__ void operator()(const f32x4 (&acc)[2][2][4][2], const Unit& u, int wr, int wc, int fr, int fq, int par) const {
;     ...
;                 for (int mm = 0; mm < 2; ++mm) { const float* cp = rope + (size_t)(row0 + ai * HALF + (2 * mp + mm) * 16) * 32 + 8 * (fq & 1);
;                     c[mm][0] = *(const f32x4*)(cp); c[mm][1] = *(const f32x4*)(cp + 4); sn[mm][0] = *(const f32x4*)(cp + 16); sn[mm][1] = *(const f32x4*)(cp + 20); }
;             }
; #pragma unroll
;             for (int mm = 0; mm < 2; ++mm) { const int m = 2 * mp + mm;
;                 const int row = row0 + ai * HALF + m * 16; const int s = row & 4095; const float rs = rsv[ai][m];
;                 f32x4 v[2][2];
; #pragma unroll
;                 for (int bj = 0; bj < 2; ++bj)
; #pragma unroll
;                     for (int n = 0; n < 2; ++n) v[bj][n] = acc[ai][bj][m][n] * rs;
;                 if (rot) {
;                     const float sgn = (fq < 2) ? -1.f : 1.f;
; #pragma unroll
;                     for (int n = 0; n < 2; ++n)
; #pragma unroll
;                         for (int j = 0; j < 4; ++j) { const float mine = v[0][n][j]; const float other = __shfl_xor(mine, 32); v[0][n][j] = mine * c[mm][n][j] + sgn * other * sn[mm][n][j]; }
;                 }
; #pragma unroll
;                 for (int bj = 0; bj < 2; ++bj) {
;                     bf16_t* dst = base + ((size_t)((b * 8 + hh) * 4096 + s)) * 128 + cih0 + 32 * bj;
;                     *(u32x4*)dst = pack8(v[bj][0], v[bj][1]);
;                     cs[bj][0] += v[bj][0]; cs[bj][1] += v[bj][1];
;                 }
.LBB0_385:
	s_lshl_b32 s1, s3, 1
	s_and_b32 s1, s1, 6
	s_ashr_i32 s0, s2, 4
	s_or_b32 s1, s1, s89
	s_lshl_b32 s3, s0, 15
	s_lshl_b32 s6, s1, 12
	s_or_b32 s3, s6, s3
	v_and_b32_e32 v98, 0xfcf, v198
	v_or_b32_e32 v204, s3, v98
	s_ashr_i32 s91, s90, 31
	v_mov_b32_e32 v172, v206
	v_mov_b32_e32 v173, v206
	s_lshl_b64 s[6:7], s[90:91], 25
	v_ashrrev_i32_e32 v205, 31, v204
	v_mov_b32_e32 v174, v206
	v_mov_b32_e32 v175, v206
	v_pk_mul_f32 v[160:161], v[160:161], v[172:173]
	v_pk_mul_f32 v[156:157], v[156:157], v[172:173]
	v_lshl_add_u64 v[196:197], v[184:185], 0, s[6:7]
	v_lshlrev_b64 v[172:173], 8, v[204:205]
	v_mov_b32_e32 v98, v207
	v_pk_mul_f32 v[162:163], v[162:163], v[174:175]
	v_pk_mul_f32 v[158:159], v[158:159], v[174:175]
	v_lshl_add_u64 v[214:215], v[196:197], 0, v[172:173]
	v_cvt_pk_bf16_f32 v172, v168, v169
	v_cvt_pk_bf16_f32 v173, v170, v171
	v_cvt_pk_bf16_f32 v174, v164, v165
	v_cvt_pk_bf16_f32 v175, v166, v167
	v_pk_mul_f32 v[154:155], v[154:155], v[98:99] op_sel_hi:[1,0]
	v_pk_mul_f32 v[152:153], v[152:153], v[98:99] op_sel_hi:[1,0]
	v_pk_mul_f32 v[150:151], v[150:151], v[98:99] op_sel_hi:[1,0]
	s_and_b64 vcc, exec, s[42:43]
	v_pk_mul_f32 v[148:149], v[148:149], v[98:99] op_sel_hi:[1,0]
	global_store_dwordx4 v[214:215], v[172:175], off sc1
	s_nop 1
	v_cvt_pk_bf16_f32 v172, v160, v161
	v_cvt_pk_bf16_f32 v173, v162, v163
	v_cvt_pk_bf16_f32 v174, v156, v157
	v_cvt_pk_bf16_f32 v175, v158, v159
	global_store_dwordx4 v[214:215], v[172:175], off offset:64 sc1
	s_cbranch_vccnz .LBB0_387
	ds_bpermute_b32 v98, v224, v153
	ds_bpermute_b32 v174, v224, v154
	ds_bpermute_b32 v175, v224, v155
	ds_bpermute_b32 v172, v224, v152
	v_mov_b32_e32 v216, v155
	s_waitcnt lgkmcnt(0)
	v_cndmask_b32_e64 v173, v98, -v98, s[36:37]
	v_cndmask_b32_e64 v98, v174, -v174, s[36:37]
	s_waitcnt vmcnt(2)
	v_mul_f32_e32 v174, v122, v98
	ds_bpermute_b32 v98, v224, v149
	v_cndmask_b32_e64 v215, v175, -v175, s[36:37]
	v_mov_b32_e32 v217, v123
	v_mov_b32_e32 v214, v93
	v_pk_mul_f32 v[152:153], v[152:153], v[90:91]
	v_cndmask_b32_e64 v172, v172, -v172, s[36:37]
	v_pk_mul_f32 v[214:215], v[216:217], v[214:215]
	v_mul_f32_e32 v154, v154, v92
	v_mov_b32_e32 v155, v214
	v_mov_b32_e32 v175, v215
	v_pk_fma_f32 v[152:153], v[120:121], v[172:173], v[152:153]
	s_waitcnt lgkmcnt(0)
	v_cndmask_b32_e64 v173, v98, -v98, s[36:37]
	ds_bpermute_b32 v98, v224, v151
	v_pk_add_f32 v[154:155], v[154:155], v[174:175]
	ds_bpermute_b32 v174, v224, v150
	ds_bpermute_b32 v172, v224, v148
	v_mov_b32_e32 v216, v151
	s_waitcnt lgkmcnt(2)
	v_cndmask_b32_e64 v215, v98, -v98, s[36:37]
	v_mov_b32_e32 v217, v97
	v_mov_b32_e32 v214, v85
	s_waitcnt lgkmcnt(1)
	v_cndmask_b32_e64 v174, v174, -v174, s[36:37]
	v_pk_mul_f32 v[214:215], v[216:217], v[214:215]
	v_pk_mul_f32 v[148:149], v[148:149], v[82:83]
	s_waitcnt lgkmcnt(0)
	v_cndmask_b32_e64 v172, v172, -v172, s[36:37]
	v_mul_f32_e32 v150, v150, v84
	v_mul_f32_e32 v174, v96, v174
	v_mov_b32_e32 v151, v214
	v_mov_b32_e32 v175, v215
	v_pk_fma_f32 v[148:149], v[94:95], v[172:173], v[148:149]
	v_pk_add_f32 v[150:151], v[150:151], v[174:175]
.LBB0_387:
	s_nop 0
	v_mov_b32_e32 v172, v207
	v_mov_b32_e32 v173, v207
	v_pk_mul_f32 v[146:147], v[146:147], v[172:173]
	v_pk_mul_f32 v[142:143], v[142:143], v[172:173]
	v_or_b32_e32 v172, 16, v204
	v_ashrrev_i32_e32 v173, 31, v172
	v_mov_b32_e32 v206, v207
	v_lshlrev_b64 v[172:173], 8, v[172:173]
	v_pk_mul_f32 v[144:145], v[144:145], v[206:207]
	v_pk_mul_f32 v[140:141], v[140:141], v[206:207]
	v_lshl_add_u64 v[206:207], v[196:197], 0, v[172:173]
	v_cvt_pk_bf16_f32 v172, v152, v153
	v_cvt_pk_bf16_f32 v173, v154, v155
	v_cvt_pk_bf16_f32 v174, v148, v149
	v_cvt_pk_bf16_f32 v175, v150, v151
	s_and_b64 vcc, exec, s[42:43]
	global_store_dwordx4 v[206:207], v[172:175], off sc1
	s_nop 1
	v_cvt_pk_bf16_f32 v172, v144, v145
	v_cvt_pk_bf16_f32 v173, v146, v147
	v_cvt_pk_bf16_f32 v174, v140, v141
	v_cvt_pk_bf16_f32 v175, v142, v143
	global_store_dwordx4 v[206:207], v[172:175], off offset:64 sc1
	s_cbranch_vccnz .LBB0_389
	s_waitcnt vmcnt(4)
	v_or_b32_e32 v82, 32, v198
	v_ashrrev_i32_e32 v83, 31, v82
	v_lshlrev_b64 v[82:83], 7, v[82:83]
	v_lshl_add_u64 v[82:83], v[188:189], 0, v[82:83]
	global_load_dwordx4 v[100:103], v[82:83], off offset:16
	global_load_dwordx4 v[116:119], v[82:83], off
	global_load_dwordx4 v[124:127], v[82:83], off offset:80
	global_load_dwordx4 v[128:131], v[82:83], off offset:64
	v_or_b32_e32 v82, 48, v198
	v_ashrrev_i32_e32 v83, 31, v82
	v_lshlrev_b64 v[82:83], 7, v[82:83]
	v_lshl_add_u64 v[120:121], v[188:189], 0, v[82:83]
	global_load_dwordx4 v[82:85], v[120:121], off offset:16
	global_load_dwordx4 v[90:93], v[120:121], off
	global_load_dwordx4 v[94:97], v[120:121], off offset:80
	s_nop 0
	global_load_dwordx4 v[120:123], v[120:121], off offset:64

; __device__ __forceinline__ u32x4 pack8(f32x4 a, f32x4 b) { u32x4 w; w.x = cvt_pk_bf16(a[0], a[1]); w.y = cvt_pk_bf16(a[2], a[3]); w.z = cvt_pk_bf16(b[0], b[1]); w.w = cvt_pk_bf16(b[2], b[3]); return w; }
; __device__ __forceinline__ bf16x8 pack8(f32x4 a, f32x4 b) { u32x4 w = {cvtpk(a[0], a[1]), cvtpk(a[2], a[3]), cvtpk(b[0], b[1]), cvtpk(b[2], b[3])}; return *reinterpret_cast<bf16x8*>(&w); }
;     PG8_RSTD_HOOKS
;     __device__ __forceinline__ void operator()(const f32x4 (&acc)[2][2][4][2], const Unit& u, int wr, int wc, int fr, int fq, int par) const {
;     ...
;                 for (int mm = 0; mm < 2; ++mm) { const float* cp = rope + (size_t)(row0 + ai * HALF + (2 * mp + mm) * 16) * 32 + 8 * (fq & 1);
;                     c[mm][0] = *(const f32x4*)(cp); c[mm][1] = *(const f32x4*)(cp + 4); sn[mm][0] = *(const f32x4*)(cp + 16); sn[mm][1] = *(const f32x4*)(cp + 20); }
;             }
; #pragma unroll
;             for (int mm = 0; mm < 2; ++mm) { const int m = 2 * mp + mm;
;                 const int row = row0 + ai * HALF + m * 16; const int s = row & 4095; const float rs = rsv[ai][m];
;                 f32x4 v[2][2];
; #pragma unroll
;                 for (int bj = 0; bj < 2; ++bj)
; #pragma unroll
;                     for (int n = 0; n < 2; ++n) v[bj][n] = acc[ai][bj][m][n] * rs;
;                 if (rot) {
;                     const float sgn = (fq < 2) ? -1.f : 1.f;
; #pragma unroll
;                     for (int n = 0; n < 2; ++n)
; #pragma unroll
;                         for (int j = 0; j < 4; ++j) { const float mine = v[0][n][j]; const float other = __shfl_xor(mine, 32); v[0][n][j] = mine * c[mm][n][j] + sgn * other * sn[mm][n][j]; }
;                 }
; #pragma unroll
;                 for (int bj = 0; bj < 2; ++bj) {
;                     bf16_t* dst = base + ((size_t)((b * 8 + hh) * 4096 + s)) * 128 + cih0 + 32 * bj;
;                     *(u32x4*)dst = pack8(v[bj][0], v[bj][1]);
;                     cs[bj][0] += v[bj][0]; cs[bj][1] += v[bj][1];
;                 }
.LBB0_391:
	v_mov_b32_e32 v172, v202
	v_mov_b32_e32 v173, v202
	v_pk_mul_f32 v[112:113], v[112:113], v[172:173]
	v_pk_mul_f32 v[108:109], v[108:109], v[172:173]
	v_or_b32_e32 v172, 32, v204
	v_ashrrev_i32_e32 v173, 31, v172
	v_mov_b32_e32 v174, v202
	v_mov_b32_e32 v175, v202
	v_lshlrev_b64 v[172:173], 8, v[172:173]
	v_mov_b32_e32 v98, v203
	v_pk_mul_f32 v[114:115], v[114:115], v[174:175]
	v_pk_mul_f32 v[110:111], v[110:111], v[174:175]
	v_lshl_add_u64 v[206:207], v[196:197], 0, v[172:173]
	v_cvt_pk_bf16_f32 v172, v136, v137
	v_cvt_pk_bf16_f32 v173, v138, v139
	v_cvt_pk_bf16_f32 v174, v132, v133
	v_cvt_pk_bf16_f32 v175, v134, v135
	v_pk_mul_f32 v[106:107], v[106:107], v[98:99] op_sel_hi:[1,0]
	v_pk_mul_f32 v[104:105], v[104:105], v[98:99] op_sel_hi:[1,0]
	v_pk_mul_f32 v[88:89], v[88:89], v[98:99] op_sel_hi:[1,0]
	s_and_b64 vcc, exec, s[42:43]
	v_pk_mul_f32 v[86:87], v[86:87], v[98:99] op_sel_hi:[1,0]
	global_store_dwordx4 v[206:207], v[172:175], off sc1
	s_nop 1
	v_cvt_pk_bf16_f32 v172, v112, v113
	v_cvt_pk_bf16_f32 v173, v114, v115
	v_cvt_pk_bf16_f32 v174, v108, v109
	v_cvt_pk_bf16_f32 v175, v110, v111
	global_store_dwordx4 v[206:207], v[172:175], off offset:64 sc1
	s_cbranch_vccnz .LBB0_393
	ds_bpermute_b32 v98, v224, v105
	ds_bpermute_b32 v174, v224, v106
	ds_bpermute_b32 v175, v224, v107
	ds_bpermute_b32 v172, v224, v104
	v_mov_b32_e32 v214, v107
	s_waitcnt lgkmcnt(0)
	v_cndmask_b32_e64 v173, v98, -v98, s[36:37]
	v_cndmask_b32_e64 v98, v174, -v174, s[36:37]
	s_waitcnt vmcnt(2)
	v_mul_f32_e32 v174, v122, v98
	ds_bpermute_b32 v98, v224, v87
	v_cndmask_b32_e64 v207, v175, -v175, s[36:37]
	v_mov_b32_e32 v215, v123
	v_mov_b32_e32 v206, v93
	v_pk_mul_f32 v[104:105], v[104:105], v[90:91]
	v_cndmask_b32_e64 v172, v172, -v172, s[36:37]
	v_pk_mul_f32 v[206:207], v[214:215], v[206:207]
	v_mul_f32_e32 v106, v106, v92
	v_mov_b32_e32 v107, v206
	v_mov_b32_e32 v175, v207
	v_pk_fma_f32 v[104:105], v[120:121], v[172:173], v[104:105]
	s_waitcnt lgkmcnt(0)
	v_cndmask_b32_e64 v173, v98, -v98, s[36:37]
	ds_bpermute_b32 v98, v224, v89
	v_pk_add_f32 v[106:107], v[106:107], v[174:175]
	ds_bpermute_b32 v174, v224, v88
	ds_bpermute_b32 v172, v224, v86
	v_mov_b32_e32 v214, v89
	s_waitcnt lgkmcnt(2)
	v_cndmask_b32_e64 v207, v98, -v98, s[36:37]
	v_mov_b32_e32 v215, v97
	v_mov_b32_e32 v206, v85
	s_waitcnt lgkmcnt(1)
	v_cndmask_b32_e64 v174, v174, -v174, s[36:37]
	v_pk_mul_f32 v[206:207], v[214:215], v[206:207]
	v_pk_mul_f32 v[86:87], v[86:87], v[82:83]
	s_waitcnt lgkmcnt(0)
	v_cndmask_b32_e64 v172, v172, -v172, s[36:37]
	v_mul_f32_e32 v88, v88, v84
	v_mul_f32_e32 v174, v96, v174
	v_mov_b32_e32 v89, v206
	v_mov_b32_e32 v175, v207
	v_pk_fma_f32 v[86:87], v[94:95], v[172:173], v[86:87]
	v_pk_add_f32 v[88:89], v[88:89], v[174:175]
.LBB0_393:
	s_nop 0
	v_mov_b32_e32 v172, v203
	v_mov_b32_e32 v173, v203
	v_pk_mul_f32 v[80:81], v[80:81], v[172:173]
	v_pk_mul_f32 v[76:77], v[76:77], v[172:173]
	v_or_b32_e32 v172, 48, v204
	v_ashrrev_i32_e32 v173, 31, v172
	v_mov_b32_e32 v202, v203
	v_lshlrev_b64 v[172:173], 8, v[172:173]
	v_pk_mul_f32 v[78:79], v[78:79], v[202:203]
	v_pk_mul_f32 v[74:75], v[74:75], v[202:203]
	v_lshl_add_u64 v[202:203], v[196:197], 0, v[172:173]
	v_cvt_pk_bf16_f32 v172, v104, v105
	v_cvt_pk_bf16_f32 v173, v106, v107
	v_cvt_pk_bf16_f32 v174, v86, v87
	v_cvt_pk_bf16_f32 v175, v88, v89
	s_and_b64 vcc, exec, s[42:43]
	v_add_u32_e32 v204, 0x80, v198
	global_store_dwordx4 v[202:203], v[172:175], off sc1
	s_nop 1
	v_cvt_pk_bf16_f32 v172, v78, v79
	v_cvt_pk_bf16_f32 v173, v80, v81
	v_cvt_pk_bf16_f32 v174, v74, v75
	v_cvt_pk_bf16_f32 v175, v76, v77
	global_store_dwordx4 v[202:203], v[172:175], off offset:64 sc1
	s_cbranch_vccnz .LBB0_395
	v_ashrrev_i32_e32 v205, 31, v204
	s_waitcnt vmcnt(4)
	v_lshlrev_b64 v[82:83], 7, v[204:205]
	v_lshl_add_u64 v[82:83], v[188:189], 0, v[82:83]
	global_load_dwordx4 v[100:103], v[82:83], off offset:16
	global_load_dwordx4 v[116:119], v[82:83], off
	global_load_dwordx4 v[124:127], v[82:83], off offset:80
	global_load_dwordx4 v[128:131], v[82:83], off offset:64
	v_lshlrev_b64 v[82:83], 7, v[198:199]
	v_lshl_add_u64 v[82:83], v[188:189], 0, v[82:83]
	s_mov_b64 s[6:7], 0x4800
	v_lshl_add_u64 v[120:121], v[82:83], 0, s[6:7]
	s_movk_i32 s6, 0x4000
	v_add_co_u32_e32 v82, vcc, s6, v82
	s_nop 1
	v_addc_co_u32_e32 v83, vcc, 0, v83, vcc
	global_load_dwordx4 v[90:93], v[82:83], off offset:2048
	global_load_dwordx4 v[94:97], v[120:121], off offset:80
	s_nop 0
	global_load_dwordx4 v[82:85], v[120:121], off offset:16
	s_nop 0
	global_load_dwordx4 v[120:123], v[120:121], off offset:64

; __device__ __forceinline__ u32x4 pack8(f32x4 a, f32x4 b) { u32x4 w; w.x = cvt_pk_bf16(a[0], a[1]); w.y = cvt_pk_bf16(a[2], a[3]); w.z = cvt_pk_bf16(b[0], b[1]); w.w = cvt_pk_bf16(b[2], b[3]); return w; }
; __device__ __forceinline__ bf16x8 pack8(f32x4 a, f32x4 b) { u32x4 w = {cvtpk(a[0], a[1]), cvtpk(a[2], a[3]), cvtpk(b[0], b[1]), cvtpk(b[2], b[3])}; return *reinterpret_cast<bf16x8*>(&w); }
;     PG8_RSTD_HOOKS
;     __device__ __forceinline__ void operator()(const f32x4 (&acc)[2][2][4][2], const Unit& u, int wr, int wc, int fr, int fq, int par) const {
;     ...
;                 for (int mm = 0; mm < 2; ++mm) { const float* cp = rope + (size_t)(row0 + ai * HALF + (2 * mp + mm) * 16) * 32 + 8 * (fq & 1);
;                     c[mm][0] = *(const f32x4*)(cp); c[mm][1] = *(const f32x4*)(cp + 4); sn[mm][0] = *(const f32x4*)(cp + 16); sn[mm][1] = *(const f32x4*)(cp + 20); }
;             }
; #pragma unroll
;             for (int mm = 0; mm < 2; ++mm) { const int m = 2 * mp + mm;
;                 const int row = row0 + ai * HALF + m * 16; const int s = row & 4095; const float rs = rsv[ai][m];
;                 f32x4 v[2][2];
; #pragma unroll
;                 for (int bj = 0; bj < 2; ++bj)
; #pragma unroll
;                     for (int n = 0; n < 2; ++n) v[bj][n] = acc[ai][bj][m][n] * rs;
;                 if (rot) {
;                     const float sgn = (fq < 2) ? -1.f : 1.f;
; #pragma unroll
;                     for (int n = 0; n < 2; ++n)
; #pragma unroll
;                         for (int j = 0; j < 4; ++j) { const float mine = v[0][n][j]; const float other = __shfl_xor(mine, 32); v[0][n][j] = mine * c[mm][n][j] + sgn * other * sn[mm][n][j]; }
;                 }
; #pragma unroll
;                 for (int bj = 0; bj < 2; ++bj) {
;                     bf16_t* dst = base + ((size_t)((b * 8 + hh) * 4096 + s)) * 128 + cih0 + 32 * bj;
;                     *(u32x4*)dst = pack8(v[bj][0], v[bj][1]);
;                     cs[bj][0] += v[bj][0]; cs[bj][1] += v[bj][1];
;                 }
.LBB0_397:
	v_and_b32_e32 v98, 0xfcf, v204
	v_or_b32_e32 v202, s3, v98
	v_mov_b32_e32 v172, v200
	v_mov_b32_e32 v173, v200
	v_ashrrev_i32_e32 v203, 31, v202
	v_mov_b32_e32 v174, v200
	v_mov_b32_e32 v175, v200
	v_pk_mul_f32 v[62:63], v[62:63], v[172:173]
	v_pk_mul_f32 v[58:59], v[58:59], v[172:173]
	v_lshlrev_b64 v[172:173], 8, v[202:203]
	v_mov_b32_e32 v98, v201
	v_pk_mul_f32 v[64:65], v[64:65], v[174:175]
	v_pk_mul_f32 v[60:61], v[60:61], v[174:175]
	v_lshl_add_u64 v[206:207], v[196:197], 0, v[172:173]
	v_cvt_pk_bf16_f32 v172, v70, v71
	v_cvt_pk_bf16_f32 v173, v72, v73
	v_cvt_pk_bf16_f32 v174, v66, v67
	v_cvt_pk_bf16_f32 v175, v68, v69
	v_pk_mul_f32 v[56:57], v[56:57], v[98:99] op_sel_hi:[1,0]
	v_pk_mul_f32 v[54:55], v[54:55], v[98:99] op_sel_hi:[1,0]
	v_pk_mul_f32 v[52:53], v[52:53], v[98:99] op_sel_hi:[1,0]
	s_and_b64 vcc, exec, s[42:43]
	v_pk_mul_f32 v[50:51], v[50:51], v[98:99] op_sel_hi:[1,0]
	global_store_dwordx4 v[206:207], v[172:175], off sc1
	s_nop 1
	v_cvt_pk_bf16_f32 v172, v62, v63
	v_cvt_pk_bf16_f32 v173, v64, v65
	v_cvt_pk_bf16_f32 v174, v58, v59
	v_cvt_pk_bf16_f32 v175, v60, v61
	global_store_dwordx4 v[206:207], v[172:175], off offset:64 sc1
	s_cbranch_vccnz .LBB0_399
	ds_bpermute_b32 v98, v224, v55
	ds_bpermute_b32 v174, v224, v56
	ds_bpermute_b32 v175, v224, v57
	ds_bpermute_b32 v172, v224, v54
	v_mov_b32_e32 v214, v57
	s_waitcnt lgkmcnt(0)
	v_cndmask_b32_e64 v173, v98, -v98, s[36:37]
	v_cndmask_b32_e64 v98, v174, -v174, s[36:37]
	s_waitcnt vmcnt(2)
	v_mul_f32_e32 v174, v122, v98
	ds_bpermute_b32 v98, v224, v51
	v_cndmask_b32_e64 v207, v175, -v175, s[36:37]
	v_mov_b32_e32 v215, v123
	v_mov_b32_e32 v206, v93
	v_pk_mul_f32 v[54:55], v[54:55], v[90:91]
	v_cndmask_b32_e64 v172, v172, -v172, s[36:37]
	v_pk_mul_f32 v[206:207], v[214:215], v[206:207]
	v_mul_f32_e32 v56, v56, v92
	v_mov_b32_e32 v57, v206
	v_mov_b32_e32 v175, v207
	v_pk_fma_f32 v[54:55], v[120:121], v[172:173], v[54:55]
	s_waitcnt lgkmcnt(0)
	v_cndmask_b32_e64 v173, v98, -v98, s[36:37]
	ds_bpermute_b32 v98, v224, v53
	v_pk_add_f32 v[56:57], v[56:57], v[174:175]
	ds_bpermute_b32 v174, v224, v52
	ds_bpermute_b32 v172, v224, v50
	v_mov_b32_e32 v214, v53
	s_waitcnt lgkmcnt(2)
	v_cndmask_b32_e64 v207, v98, -v98, s[36:37]
	v_mov_b32_e32 v215, v97
	v_mov_b32_e32 v206, v85
	s_waitcnt lgkmcnt(1)
	v_cndmask_b32_e64 v174, v174, -v174, s[36:37]
	v_pk_mul_f32 v[206:207], v[214:215], v[206:207]
	v_pk_mul_f32 v[50:51], v[50:51], v[82:83]
	s_waitcnt lgkmcnt(0)
	v_cndmask_b32_e64 v172, v172, -v172, s[36:37]
	v_mul_f32_e32 v52, v52, v84
	v_mul_f32_e32 v174, v96, v174
	v_mov_b32_e32 v53, v206
	v_mov_b32_e32 v175, v207
	v_pk_fma_f32 v[50:51], v[94:95], v[172:173], v[50:51]
	v_pk_add_f32 v[52:53], v[52:53], v[174:175]
.LBB0_399:
	s_nop 0
	v_mov_b32_e32 v172, v201
	v_mov_b32_e32 v173, v201
	v_pk_mul_f32 v[48:49], v[48:49], v[172:173]
	v_pk_mul_f32 v[44:45], v[44:45], v[172:173]
	v_or_b32_e32 v172, 16, v202
	v_ashrrev_i32_e32 v173, 31, v172
	v_mov_b32_e32 v200, v201
	v_lshlrev_b64 v[172:173], 8, v[172:173]
	v_pk_mul_f32 v[46:47], v[46:47], v[200:201]
	v_pk_mul_f32 v[42:43], v[42:43], v[200:201]
	v_lshl_add_u64 v[200:201], v[196:197], 0, v[172:173]
	v_cvt_pk_bf16_f32 v172, v54, v55
	v_cvt_pk_bf16_f32 v173, v56, v57
	v_cvt_pk_bf16_f32 v174, v50, v51
	v_cvt_pk_bf16_f32 v175, v52, v53
	s_and_b64 vcc, exec, s[42:43]
	global_store_dwordx4 v[200:201], v[172:175], off sc1
	s_nop 1
	v_cvt_pk_bf16_f32 v172, v46, v47
	v_cvt_pk_bf16_f32 v173, v48, v49
	v_cvt_pk_bf16_f32 v174, v42, v43
	v_cvt_pk_bf16_f32 v175, v44, v45
	global_store_dwordx4 v[200:201], v[172:175], off offset:64 sc1
	s_cbranch_vccnz .LBB0_401
	s_waitcnt vmcnt(4)
	v_or_b32_e32 v82, 32, v204
	v_ashrrev_i32_e32 v83, 31, v82
	v_lshlrev_b64 v[82:83], 7, v[82:83]
	v_lshl_add_u64 v[82:83], v[188:189], 0, v[82:83]
	global_load_dwordx4 v[100:103], v[82:83], off offset:16
	global_load_dwordx4 v[116:119], v[82:83], off
	global_load_dwordx4 v[124:127], v[82:83], off offset:80
	global_load_dwordx4 v[128:131], v[82:83], off offset:64
	v_lshlrev_b64 v[82:83], 7, v[198:199]
	v_lshl_add_u64 v[82:83], v[188:189], 0, v[82:83]
	s_mov_b64 s[6:7], 0x5800
	s_movk_i32 s3, 0x5000
	v_lshl_add_u64 v[120:121], v[82:83], 0, s[6:7]
	v_add_co_u32_e32 v82, vcc, s3, v82
	s_nop 1
	v_addc_co_u32_e32 v83, vcc, 0, v83, vcc
	global_load_dwordx4 v[90:93], v[82:83], off offset:2048
	global_load_dwordx4 v[94:97], v[120:121], off offset:80
	s_nop 0
	global_load_dwordx4 v[82:85], v[120:121], off offset:16
	s_nop 0
	global_load_dwordx4 v[120:123], v[120:121], off offset:64
